# same code as the best version with the unreachable replaced hipcc epilogue bodies of ffn1/xq/xo deleted (2767 lines)
# speedup vs baseline: 1.0022x; 1.0022x over previous
.LBB0_40:
	v_readlane_b32 s4, v250, 25
	v_mbcnt_lo_u32_b32 v147, -1, 0
	v_mbcnt_hi_u32_b32 v147, -1, v147
	s_nop 1
	s_lshr_b32 s5, s4, 8
	s_bfe_u32 s4, s4, 0x20006
	v_and_b32_e32 v148, 15, v147
	v_lshrrev_b32_e32 v149, 4, v147
	s_lshl_b32 s70, s28, 8
	s_lshl_b32 s5, s5, 6
	s_add_u32 s5, s5, s70
	v_add_u32_e32 v148, s5, v148
	v_lshlrev_b32_e32 v139, 6, v148
	v_lshl_add_u32 v139, v149, 4, v139
	v_lshlrev_b32_e32 v138, 13, v148
	v_lshl_add_u32 v138, v149, 4, v138
	s_lshl_b32 s4, s4, 6
	v_add_u32_e32 v138, s4, v138
	s_lshl_b32 s70, s25, 9
	s_add_u32 s54, s80, s70
	s_addc_u32 s55, s81, 0
	v_readlane_b32 s74, v250, 26
	v_readlane_b32 s75, v250, 27
	s_nop 4
	global_load_dwordx4 v[154:157], v139, s[74:75]
	global_load_dwordx4 v[158:161], v139, s[74:75] offset:1024
	global_load_dwordx4 v[162:165], v139, s[74:75] offset:2048
	global_load_dwordx4 v[166:169], v139, s[74:75] offset:3072
	v_add_u32_e32 v139, 0x2000, v139
	s_waitcnt vmcnt(0)
	v_add_f32_e32 v154, v154, v155
	v_add_f32_e32 v156, v156, v157
	v_add_f32_e32 v147, v154, v156
	v_add_f32_e32 v158, v158, v159
	v_add_f32_e32 v160, v160, v161
	v_add_f32_e32 v148, v158, v160
	v_add_f32_e32 v162, v162, v163
	v_add_f32_e32 v164, v164, v165
	v_add_f32_e32 v149, v162, v164
	v_add_f32_e32 v166, v166, v167
	v_add_f32_e32 v168, v168, v169
	v_add_f32_e32 v171, v166, v168
	global_load_dwordx4 v[154:157], v139, s[74:75]
	global_load_dwordx4 v[158:161], v139, s[74:75] offset:1024
	global_load_dwordx4 v[162:165], v139, s[74:75] offset:2048
	global_load_dwordx4 v[166:169], v139, s[74:75] offset:3072
	v_mov_b32_e32 v170, v147
	s_nop 1
	v_permlane16_swap_b32_e32 v170, v147
	v_add_f32_e32 v147, v170, v147
	v_mov_b32_e32 v170, v148
	s_nop 1
	v_permlane16_swap_b32_e32 v170, v148
	v_add_f32_e32 v148, v170, v148
	v_mov_b32_e32 v170, v149
	s_nop 1
	v_permlane16_swap_b32_e32 v170, v149
	v_add_f32_e32 v149, v170, v149
	v_mov_b32_e32 v170, v171
	s_nop 1
	v_permlane16_swap_b32_e32 v170, v171
	v_add_f32_e32 v171, v170, v171
	v_mov_b32_e32 v170, v147
	s_nop 1
	v_permlane32_swap_b32_e32 v170, v147
	v_add_f32_e32 v147, v170, v147
	v_mov_b32_e32 v170, v148
	s_nop 1
	v_permlane32_swap_b32_e32 v170, v148
	v_add_f32_e32 v148, v170, v148
	v_mov_b32_e32 v170, v149
	s_nop 1
	v_permlane32_swap_b32_e32 v170, v149
	v_add_f32_e32 v149, v170, v149
	v_mov_b32_e32 v170, v171
	s_nop 1
	v_permlane32_swap_b32_e32 v170, v171
	v_add_f32_e32 v171, v170, v171
	v_fmamk_f32 v147, v147, 0x3a800000, v176
	v_fmamk_f32 v148, v148, 0x3a800000, v176
	v_fmamk_f32 v149, v149, 0x3a800000, v176
	v_fmamk_f32 v171, v171, 0x3a800000, v176
	v_rsq_f32_e32 v147, v147
	v_rsq_f32_e32 v148, v148
	v_rsq_f32_e32 v149, v149
	v_rsq_f32_e32 v171, v171
	s_nop 0
	v_mul_f32_e32 v147, v147, v147
	v_mul_f32_e32 v148, v148, v148
	v_mul_f32_e32 v149, v149, v149
	v_mul_f32_e32 v171, v171, v171
	s_waitcnt vmcnt(0)
	v_add_f32_e32 v154, v154, v155
	v_add_f32_e32 v156, v156, v157
	v_add_f32_e32 v154, v154, v156
	v_add_f32_e32 v158, v158, v159
	v_add_f32_e32 v160, v160, v161
	v_add_f32_e32 v158, v158, v160
	v_add_f32_e32 v162, v162, v163
	v_add_f32_e32 v164, v164, v165
	v_add_f32_e32 v162, v162, v164
	v_add_f32_e32 v166, v166, v167
	v_add_f32_e32 v168, v168, v169
	v_add_f32_e32 v166, v166, v168
	v_mov_b32_e32 v170, v154
	s_nop 1
	v_permlane16_swap_b32_e32 v170, v154
	v_add_f32_e32 v154, v170, v154
	v_mov_b32_e32 v170, v158
	s_nop 1
	v_permlane16_swap_b32_e32 v170, v158
	v_add_f32_e32 v158, v170, v158
	v_mov_b32_e32 v170, v162
	s_nop 1
	v_permlane16_swap_b32_e32 v170, v162
	v_add_f32_e32 v162, v170, v162
	v_mov_b32_e32 v170, v166
	s_nop 1
	v_permlane16_swap_b32_e32 v170, v166
	v_add_f32_e32 v166, v170, v166
	v_mov_b32_e32 v170, v154
	s_nop 1
	v_permlane32_swap_b32_e32 v170, v154
	v_add_f32_e32 v154, v170, v154
	v_mov_b32_e32 v170, v158
	s_nop 1
	v_permlane32_swap_b32_e32 v170, v158
	v_add_f32_e32 v158, v170, v158
	v_mov_b32_e32 v170, v162
	s_nop 1
	v_permlane32_swap_b32_e32 v170, v162
	v_add_f32_e32 v162, v170, v162
	v_mov_b32_e32 v170, v166
	s_nop 1
	v_permlane32_swap_b32_e32 v170, v166
	v_add_f32_e32 v166, v170, v166
	v_fmamk_f32 v154, v154, 0x3a800000, v176
	v_fmamk_f32 v158, v158, 0x3a800000, v176
	v_fmamk_f32 v162, v162, 0x3a800000, v176
	v_fmamk_f32 v166, v166, 0x3a800000, v176
	v_rsq_f32_e32 v154, v154
	v_rsq_f32_e32 v158, v158
	v_rsq_f32_e32 v162, v162
	v_rsq_f32_e32 v166, v166
	s_nop 0
	v_mul_f32_e32 v154, v154, v154
	v_mul_f32_e32 v158, v158, v158
	v_mul_f32_e32 v162, v162, v162
	v_mul_f32_e32 v166, v166, v166
	v_max_f32_e32 v126, 0, v126
	v_max_f32_e32 v127, 0, v127
	v_max_f32_e32 v128, 0, v128
	v_max_f32_e32 v129, 0, v129
	v_max_f32_e32 v122, 0, v122
	v_max_f32_e32 v123, 0, v123
	v_max_f32_e32 v124, 0, v124
	v_max_f32_e32 v125, 0, v125
	v_pk_mul_f32 v[126:127], v[126:127], v[126:127]
	v_pk_mul_f32 v[128:129], v[128:129], v[128:129]
	v_pk_mul_f32 v[122:123], v[122:123], v[122:123]
	v_pk_mul_f32 v[124:125], v[124:125], v[124:125]
	v_mul_f32_e32 v126, v126, v147
	v_mul_f32_e32 v127, v127, v147
	v_mul_f32_e32 v128, v128, v147
	v_mul_f32_e32 v129, v129, v147
	v_mul_f32_e32 v122, v122, v147
	v_mul_f32_e32 v123, v123, v147
	v_mul_f32_e32 v124, v124, v147
	v_mul_f32_e32 v125, v125, v147
	v_cvt_pk_bf16_f32 v126, v126, v127
	v_cvt_pk_bf16_f32 v127, v128, v129
	v_cvt_pk_bf16_f32 v128, v122, v123
	v_cvt_pk_bf16_f32 v129, v124, v125
	global_store_dwordx4 v138, v[126:129], s[54:55]
	v_max_f32_e32 v118, 0, v118
	v_max_f32_e32 v119, 0, v119
	v_max_f32_e32 v120, 0, v120
	v_max_f32_e32 v121, 0, v121
	v_max_f32_e32 v114, 0, v114
	v_max_f32_e32 v115, 0, v115
	v_max_f32_e32 v116, 0, v116
	v_max_f32_e32 v117, 0, v117
	v_pk_mul_f32 v[118:119], v[118:119], v[118:119]
	v_pk_mul_f32 v[120:121], v[120:121], v[120:121]
	v_pk_mul_f32 v[114:115], v[114:115], v[114:115]
	v_pk_mul_f32 v[116:117], v[116:117], v[116:117]
	v_mul_f32_e32 v118, v118, v147
	v_mul_f32_e32 v119, v119, v147
	v_mul_f32_e32 v120, v120, v147
	v_mul_f32_e32 v121, v121, v147
	v_mul_f32_e32 v114, v114, v147
	v_mul_f32_e32 v115, v115, v147
	v_mul_f32_e32 v116, v116, v147
	v_mul_f32_e32 v117, v117, v147
	v_cvt_pk_bf16_f32 v118, v118, v119
	v_cvt_pk_bf16_f32 v119, v120, v121
	v_cvt_pk_bf16_f32 v120, v114, v115
	v_cvt_pk_bf16_f32 v121, v116, v117
	global_store_dwordx4 v138, v[118:121], s[54:55] offset:256
	v_add_u32_e32 v138, 0x20000, v138
	v_max_f32_e32 v110, 0, v110
	v_max_f32_e32 v111, 0, v111
	v_max_f32_e32 v112, 0, v112
	v_max_f32_e32 v113, 0, v113
	v_max_f32_e32 v106, 0, v106
	v_max_f32_e32 v107, 0, v107
	v_max_f32_e32 v108, 0, v108
	v_max_f32_e32 v109, 0, v109
	v_pk_mul_f32 v[110:111], v[110:111], v[110:111]
	v_pk_mul_f32 v[112:113], v[112:113], v[112:113]
	v_pk_mul_f32 v[106:107], v[106:107], v[106:107]
	v_pk_mul_f32 v[108:109], v[108:109], v[108:109]
	v_mul_f32_e32 v110, v110, v148
	v_mul_f32_e32 v111, v111, v148
	v_mul_f32_e32 v112, v112, v148
	v_mul_f32_e32 v113, v113, v148
	v_mul_f32_e32 v106, v106, v148
	v_mul_f32_e32 v107, v107, v148
	v_mul_f32_e32 v108, v108, v148
	v_mul_f32_e32 v109, v109, v148
	v_cvt_pk_bf16_f32 v110, v110, v111
	v_cvt_pk_bf16_f32 v111, v112, v113
	v_cvt_pk_bf16_f32 v112, v106, v107
	v_cvt_pk_bf16_f32 v113, v108, v109
	global_store_dwordx4 v138, v[110:113], s[54:55]
	v_max_f32_e32 v102, 0, v102
	v_max_f32_e32 v103, 0, v103
	v_max_f32_e32 v104, 0, v104
	v_max_f32_e32 v105, 0, v105
	v_max_f32_e32 v98, 0, v98
	v_max_f32_e32 v99, 0, v99
	v_max_f32_e32 v100, 0, v100
	v_max_f32_e32 v101, 0, v101
	v_pk_mul_f32 v[102:103], v[102:103], v[102:103]
	v_pk_mul_f32 v[104:105], v[104:105], v[104:105]
	v_pk_mul_f32 v[98:99], v[98:99], v[98:99]
	v_pk_mul_f32 v[100:101], v[100:101], v[100:101]
	v_mul_f32_e32 v102, v102, v148
	v_mul_f32_e32 v103, v103, v148
	v_mul_f32_e32 v104, v104, v148
	v_mul_f32_e32 v105, v105, v148
	v_mul_f32_e32 v98, v98, v148
	v_mul_f32_e32 v99, v99, v148
	v_mul_f32_e32 v100, v100, v148
	v_mul_f32_e32 v101, v101, v148
	v_cvt_pk_bf16_f32 v102, v102, v103
	v_cvt_pk_bf16_f32 v103, v104, v105
	v_cvt_pk_bf16_f32 v104, v98, v99
	v_cvt_pk_bf16_f32 v105, v100, v101
	global_store_dwordx4 v138, v[102:105], s[54:55] offset:256
	v_add_u32_e32 v138, 0x20000, v138
	v_max_f32_e32 v94, 0, v94
	v_max_f32_e32 v95, 0, v95
	v_max_f32_e32 v96, 0, v96
	v_max_f32_e32 v97, 0, v97
	v_max_f32_e32 v90, 0, v90
	v_max_f32_e32 v91, 0, v91
	v_max_f32_e32 v92, 0, v92
	v_max_f32_e32 v93, 0, v93
	v_pk_mul_f32 v[94:95], v[94:95], v[94:95]
	v_pk_mul_f32 v[96:97], v[96:97], v[96:97]
	v_pk_mul_f32 v[90:91], v[90:91], v[90:91]
	v_pk_mul_f32 v[92:93], v[92:93], v[92:93]
	v_mul_f32_e32 v94, v94, v149
	v_mul_f32_e32 v95, v95, v149
	v_mul_f32_e32 v96, v96, v149
	v_mul_f32_e32 v97, v97, v149
	v_mul_f32_e32 v90, v90, v149
	v_mul_f32_e32 v91, v91, v149
	v_mul_f32_e32 v92, v92, v149
	v_mul_f32_e32 v93, v93, v149
	v_cvt_pk_bf16_f32 v94, v94, v95
	v_cvt_pk_bf16_f32 v95, v96, v97
	v_cvt_pk_bf16_f32 v96, v90, v91
	v_cvt_pk_bf16_f32 v97, v92, v93
	global_store_dwordx4 v138, v[94:97], s[54:55]
	v_max_f32_e32 v86, 0, v86
	v_max_f32_e32 v87, 0, v87
	v_max_f32_e32 v88, 0, v88
	v_max_f32_e32 v89, 0, v89
	v_max_f32_e32 v82, 0, v82
	v_max_f32_e32 v83, 0, v83
	v_max_f32_e32 v84, 0, v84
	v_max_f32_e32 v85, 0, v85
	v_pk_mul_f32 v[86:87], v[86:87], v[86:87]
	v_pk_mul_f32 v[88:89], v[88:89], v[88:89]
	v_pk_mul_f32 v[82:83], v[82:83], v[82:83]
	v_pk_mul_f32 v[84:85], v[84:85], v[84:85]
	v_mul_f32_e32 v86, v86, v149
	v_mul_f32_e32 v87, v87, v149
	v_mul_f32_e32 v88, v88, v149
	v_mul_f32_e32 v89, v89, v149
	v_mul_f32_e32 v82, v82, v149
	v_mul_f32_e32 v83, v83, v149
	v_mul_f32_e32 v84, v84, v149
	v_mul_f32_e32 v85, v85, v149
	v_cvt_pk_bf16_f32 v86, v86, v87
	v_cvt_pk_bf16_f32 v87, v88, v89
	v_cvt_pk_bf16_f32 v88, v82, v83
	v_cvt_pk_bf16_f32 v89, v84, v85
	global_store_dwordx4 v138, v[86:89], s[54:55] offset:256
	v_add_u32_e32 v138, 0x20000, v138
	v_max_f32_e32 v78, 0, v78
	v_max_f32_e32 v79, 0, v79
	v_max_f32_e32 v80, 0, v80
	v_max_f32_e32 v81, 0, v81
	v_max_f32_e32 v74, 0, v74
	v_max_f32_e32 v75, 0, v75
	v_max_f32_e32 v76, 0, v76
	v_max_f32_e32 v77, 0, v77
	v_pk_mul_f32 v[78:79], v[78:79], v[78:79]
	v_pk_mul_f32 v[80:81], v[80:81], v[80:81]
	v_pk_mul_f32 v[74:75], v[74:75], v[74:75]
	v_pk_mul_f32 v[76:77], v[76:77], v[76:77]
	v_mul_f32_e32 v78, v78, v171
	v_mul_f32_e32 v79, v79, v171
	v_mul_f32_e32 v80, v80, v171
	v_mul_f32_e32 v81, v81, v171
	v_mul_f32_e32 v74, v74, v171
	v_mul_f32_e32 v75, v75, v171
	v_mul_f32_e32 v76, v76, v171
	v_mul_f32_e32 v77, v77, v171
	v_cvt_pk_bf16_f32 v78, v78, v79
	v_cvt_pk_bf16_f32 v79, v80, v81
	v_cvt_pk_bf16_f32 v80, v74, v75
	v_cvt_pk_bf16_f32 v81, v76, v77
	global_store_dwordx4 v138, v[78:81], s[54:55]
	v_max_f32_e32 v70, 0, v70
	v_max_f32_e32 v71, 0, v71
	v_max_f32_e32 v72, 0, v72
	v_max_f32_e32 v73, 0, v73
	v_max_f32_e32 v66, 0, v66
	v_max_f32_e32 v67, 0, v67
	v_max_f32_e32 v68, 0, v68
	v_max_f32_e32 v69, 0, v69
	v_pk_mul_f32 v[70:71], v[70:71], v[70:71]
	v_pk_mul_f32 v[72:73], v[72:73], v[72:73]
	v_pk_mul_f32 v[66:67], v[66:67], v[66:67]
	v_pk_mul_f32 v[68:69], v[68:69], v[68:69]
	v_mul_f32_e32 v70, v70, v171
	v_mul_f32_e32 v71, v71, v171
	v_mul_f32_e32 v72, v72, v171
	v_mul_f32_e32 v73, v73, v171
	v_mul_f32_e32 v66, v66, v171
	v_mul_f32_e32 v67, v67, v171
	v_mul_f32_e32 v68, v68, v171
	v_mul_f32_e32 v69, v69, v171
	v_cvt_pk_bf16_f32 v70, v70, v71
	v_cvt_pk_bf16_f32 v71, v72, v73
	v_cvt_pk_bf16_f32 v72, v66, v67
	v_cvt_pk_bf16_f32 v73, v68, v69
	global_store_dwordx4 v138, v[70:73], s[54:55] offset:256
	v_add_u32_e32 v138, 0xa0000, v138
	v_max_f32_e32 v60, 0, v60
	v_max_f32_e32 v61, 0, v61
	v_max_f32_e32 v62, 0, v62
	v_max_f32_e32 v63, 0, v63
	v_max_f32_e32 v56, 0, v56
	v_max_f32_e32 v57, 0, v57
	v_max_f32_e32 v58, 0, v58
	v_max_f32_e32 v59, 0, v59
	v_pk_mul_f32 v[60:61], v[60:61], v[60:61]
	v_pk_mul_f32 v[62:63], v[62:63], v[62:63]
	v_pk_mul_f32 v[56:57], v[56:57], v[56:57]
	v_pk_mul_f32 v[58:59], v[58:59], v[58:59]
	v_mul_f32_e32 v60, v60, v154
	v_mul_f32_e32 v61, v61, v154
	v_mul_f32_e32 v62, v62, v154
	v_mul_f32_e32 v63, v63, v154
	v_mul_f32_e32 v56, v56, v154
	v_mul_f32_e32 v57, v57, v154
	v_mul_f32_e32 v58, v58, v154
	v_mul_f32_e32 v59, v59, v154
	v_cvt_pk_bf16_f32 v60, v60, v61
	v_cvt_pk_bf16_f32 v61, v62, v63
	v_cvt_pk_bf16_f32 v62, v56, v57
	v_cvt_pk_bf16_f32 v63, v58, v59
	global_store_dwordx4 v138, v[60:63], s[54:55]
	v_max_f32_e32 v52, 0, v52
	v_max_f32_e32 v53, 0, v53
	v_max_f32_e32 v54, 0, v54
	v_max_f32_e32 v55, 0, v55
	v_max_f32_e32 v48, 0, v48
	v_max_f32_e32 v49, 0, v49
	v_max_f32_e32 v50, 0, v50
	v_max_f32_e32 v51, 0, v51
	v_pk_mul_f32 v[52:53], v[52:53], v[52:53]
	v_pk_mul_f32 v[54:55], v[54:55], v[54:55]
	v_pk_mul_f32 v[48:49], v[48:49], v[48:49]
	v_pk_mul_f32 v[50:51], v[50:51], v[50:51]
	v_mul_f32_e32 v52, v52, v154
	v_mul_f32_e32 v53, v53, v154
	v_mul_f32_e32 v54, v54, v154
	v_mul_f32_e32 v55, v55, v154
	v_mul_f32_e32 v48, v48, v154
	v_mul_f32_e32 v49, v49, v154
	v_mul_f32_e32 v50, v50, v154
	v_mul_f32_e32 v51, v51, v154
	v_cvt_pk_bf16_f32 v52, v52, v53
	v_cvt_pk_bf16_f32 v53, v54, v55
	v_cvt_pk_bf16_f32 v54, v48, v49
	v_cvt_pk_bf16_f32 v55, v50, v51
	global_store_dwordx4 v138, v[52:55], s[54:55] offset:256
	v_add_u32_e32 v138, 0x20000, v138
	v_max_f32_e32 v44, 0, v44
	v_max_f32_e32 v45, 0, v45
	v_max_f32_e32 v46, 0, v46
	v_max_f32_e32 v47, 0, v47
	v_max_f32_e32 v40, 0, v40
	v_max_f32_e32 v41, 0, v41
	v_max_f32_e32 v42, 0, v42
	v_max_f32_e32 v43, 0, v43
	v_pk_mul_f32 v[44:45], v[44:45], v[44:45]
	v_pk_mul_f32 v[46:47], v[46:47], v[46:47]
	v_pk_mul_f32 v[40:41], v[40:41], v[40:41]
	v_pk_mul_f32 v[42:43], v[42:43], v[42:43]
	v_mul_f32_e32 v44, v44, v158
	v_mul_f32_e32 v45, v45, v158
	v_mul_f32_e32 v46, v46, v158
	v_mul_f32_e32 v47, v47, v158
	v_mul_f32_e32 v40, v40, v158
	v_mul_f32_e32 v41, v41, v158
	v_mul_f32_e32 v42, v42, v158
	v_mul_f32_e32 v43, v43, v158
	v_cvt_pk_bf16_f32 v44, v44, v45
	v_cvt_pk_bf16_f32 v45, v46, v47
	v_cvt_pk_bf16_f32 v46, v40, v41
	v_cvt_pk_bf16_f32 v47, v42, v43
	global_store_dwordx4 v138, v[44:47], s[54:55]
	v_max_f32_e32 v36, 0, v36
	v_max_f32_e32 v37, 0, v37
	v_max_f32_e32 v38, 0, v38
	v_max_f32_e32 v39, 0, v39
	v_max_f32_e32 v32, 0, v32
	v_max_f32_e32 v33, 0, v33
	v_max_f32_e32 v34, 0, v34
	v_max_f32_e32 v35, 0, v35
	v_pk_mul_f32 v[36:37], v[36:37], v[36:37]
	v_pk_mul_f32 v[38:39], v[38:39], v[38:39]
	v_pk_mul_f32 v[32:33], v[32:33], v[32:33]
	v_pk_mul_f32 v[34:35], v[34:35], v[34:35]
	v_mul_f32_e32 v36, v36, v158
	v_mul_f32_e32 v37, v37, v158
	v_mul_f32_e32 v38, v38, v158
	v_mul_f32_e32 v39, v39, v158
	v_mul_f32_e32 v32, v32, v158
	v_mul_f32_e32 v33, v33, v158
	v_mul_f32_e32 v34, v34, v158
	v_mul_f32_e32 v35, v35, v158
	v_cvt_pk_bf16_f32 v36, v36, v37
	v_cvt_pk_bf16_f32 v37, v38, v39
	v_cvt_pk_bf16_f32 v38, v32, v33
	v_cvt_pk_bf16_f32 v39, v34, v35
	global_store_dwordx4 v138, v[36:39], s[54:55] offset:256
	v_add_u32_e32 v138, 0x20000, v138
	v_max_f32_e32 v28, 0, v28
	v_max_f32_e32 v29, 0, v29
	v_max_f32_e32 v30, 0, v30
	v_max_f32_e32 v31, 0, v31
	v_max_f32_e32 v24, 0, v24
	v_max_f32_e32 v25, 0, v25
	v_max_f32_e32 v26, 0, v26
	v_max_f32_e32 v27, 0, v27
	v_pk_mul_f32 v[28:29], v[28:29], v[28:29]
	v_pk_mul_f32 v[30:31], v[30:31], v[30:31]
	v_pk_mul_f32 v[24:25], v[24:25], v[24:25]
	v_pk_mul_f32 v[26:27], v[26:27], v[26:27]
	v_mul_f32_e32 v28, v28, v162
	v_mul_f32_e32 v29, v29, v162
	v_mul_f32_e32 v30, v30, v162
	v_mul_f32_e32 v31, v31, v162
	v_mul_f32_e32 v24, v24, v162
	v_mul_f32_e32 v25, v25, v162
	v_mul_f32_e32 v26, v26, v162
	v_mul_f32_e32 v27, v27, v162
	v_cvt_pk_bf16_f32 v28, v28, v29
	v_cvt_pk_bf16_f32 v29, v30, v31
	v_cvt_pk_bf16_f32 v30, v24, v25
	v_cvt_pk_bf16_f32 v31, v26, v27
	global_store_dwordx4 v138, v[28:31], s[54:55]
	v_max_f32_e32 v20, 0, v20
	v_max_f32_e32 v21, 0, v21
	v_max_f32_e32 v22, 0, v22
	v_max_f32_e32 v23, 0, v23
	v_max_f32_e32 v16, 0, v16
	v_max_f32_e32 v17, 0, v17
	v_max_f32_e32 v18, 0, v18
	v_max_f32_e32 v19, 0, v19
	v_pk_mul_f32 v[20:21], v[20:21], v[20:21]
	v_pk_mul_f32 v[22:23], v[22:23], v[22:23]
	v_pk_mul_f32 v[16:17], v[16:17], v[16:17]
	v_pk_mul_f32 v[18:19], v[18:19], v[18:19]
	v_mul_f32_e32 v20, v20, v162
	v_mul_f32_e32 v21, v21, v162
	v_mul_f32_e32 v22, v22, v162
	v_mul_f32_e32 v23, v23, v162
	v_mul_f32_e32 v16, v16, v162
	v_mul_f32_e32 v17, v17, v162
	v_mul_f32_e32 v18, v18, v162
	v_mul_f32_e32 v19, v19, v162
	v_cvt_pk_bf16_f32 v20, v20, v21
	v_cvt_pk_bf16_f32 v21, v22, v23
	v_cvt_pk_bf16_f32 v22, v16, v17
	v_cvt_pk_bf16_f32 v23, v18, v19
	global_store_dwordx4 v138, v[20:23], s[54:55] offset:256
	v_add_u32_e32 v138, 0x20000, v138
	v_max_f32_e32 v12, 0, v12
	v_max_f32_e32 v13, 0, v13
	v_max_f32_e32 v14, 0, v14
	v_max_f32_e32 v15, 0, v15
	v_max_f32_e32 v8, 0, v8
	v_max_f32_e32 v9, 0, v9
	v_max_f32_e32 v10, 0, v10
	v_max_f32_e32 v11, 0, v11
	v_pk_mul_f32 v[12:13], v[12:13], v[12:13]
	v_pk_mul_f32 v[14:15], v[14:15], v[14:15]
	v_pk_mul_f32 v[8:9], v[8:9], v[8:9]
	v_pk_mul_f32 v[10:11], v[10:11], v[10:11]
	v_mul_f32_e32 v12, v12, v166
	v_mul_f32_e32 v13, v13, v166
	v_mul_f32_e32 v14, v14, v166
	v_mul_f32_e32 v15, v15, v166
	v_mul_f32_e32 v8, v8, v166
	v_mul_f32_e32 v9, v9, v166
	v_mul_f32_e32 v10, v10, v166
	v_mul_f32_e32 v11, v11, v166
	v_cvt_pk_bf16_f32 v12, v12, v13
	v_cvt_pk_bf16_f32 v13, v14, v15
	v_cvt_pk_bf16_f32 v14, v8, v9
	v_cvt_pk_bf16_f32 v15, v10, v11
	global_store_dwordx4 v138, v[12:15], s[54:55]
	v_max_f32_e32 v4, 0, v4
	v_max_f32_e32 v5, 0, v5
	v_max_f32_e32 v6, 0, v6
	v_max_f32_e32 v7, 0, v7
	v_max_f32_e32 v0, 0, v0
	v_max_f32_e32 v1, 0, v1
	v_max_f32_e32 v2, 0, v2
	v_max_f32_e32 v3, 0, v3
	v_pk_mul_f32 v[4:5], v[4:5], v[4:5]
	v_pk_mul_f32 v[6:7], v[6:7], v[6:7]
	v_pk_mul_f32 v[0:1], v[0:1], v[0:1]
	v_pk_mul_f32 v[2:3], v[2:3], v[2:3]
	v_mul_f32_e32 v4, v4, v166
	v_mul_f32_e32 v5, v5, v166
	v_mul_f32_e32 v6, v6, v166
	v_mul_f32_e32 v7, v7, v166
	v_mul_f32_e32 v0, v0, v166
	v_mul_f32_e32 v1, v1, v166
	v_mul_f32_e32 v2, v2, v166
	v_mul_f32_e32 v3, v3, v166
	v_cvt_pk_bf16_f32 v4, v4, v5
	v_cvt_pk_bf16_f32 v5, v6, v7
	v_cvt_pk_bf16_f32 v6, v0, v1
	v_cvt_pk_bf16_f32 v7, v2, v3
	global_store_dwordx4 v138, v[4:7], s[54:55] offset:256
	s_andn2_b64 vcc, exec, s[38:39]
	s_mov_b64 s[4:5], -1
	s_branch .Lffn1_done
.Lffn1_done:
	s_cbranch_vccnz .LBB0_29
	s_andn2_b64 vcc, exec, s[36:37]
	s_cbranch_vccnz .LBB0_28
	s_barrier
	s_branch .LBB0_28

.LBB0_69:
	v_readlane_b32 s36, v250, 25
	v_mbcnt_lo_u32_b32 v147, -1, 0
	v_mbcnt_hi_u32_b32 v147, -1, v147
	s_nop 1
	s_lshr_b32 s37, s36, 8
	s_bfe_u32 s36, s36, 0x20006
	v_and_b32_e32 v148, 15, v147
	v_lshrrev_b32_e32 v149, 4, v147
	s_lshl_b32 vcc_lo, s3, 8
	s_lshl_b32 s37, s37, 6
	s_add_u32 s37, s37, vcc_lo
	v_add_u32_e32 v148, s37, v148
	v_lshlrev_b32_e32 v139, 6, v148
	v_lshl_add_u32 v139, v149, 4, v139
	v_lshlrev_b32_e32 v138, 11, v148
	v_lshl_add_u32 v138, v149, 4, v138
	s_lshl_b32 s36, s36, 6
	v_add_u32_e32 v138, s36, v138
	s_lshl_b32 vcc_lo, s2, 9
	s_add_u32 s54, s80, vcc_lo
	s_addc_u32 s55, s81, 0
	v_readlane_b32 s2, v250, 23
	v_readlane_b32 s3, v250, 24
	s_nop 4
	global_load_dwordx4 v[154:157], v139, s[2:3]
	global_load_dwordx4 v[158:161], v139, s[2:3] offset:1024
	global_load_dwordx4 v[162:165], v139, s[2:3] offset:2048
	global_load_dwordx4 v[166:169], v139, s[2:3] offset:3072
	v_add_u32_e32 v139, 0x2000, v139
	s_waitcnt vmcnt(0)
	v_add_f32_e32 v154, v154, v155
	v_add_f32_e32 v156, v156, v157
	v_add_f32_e32 v147, v154, v156
	v_add_f32_e32 v158, v158, v159
	v_add_f32_e32 v160, v160, v161
	v_add_f32_e32 v148, v158, v160
	v_add_f32_e32 v162, v162, v163
	v_add_f32_e32 v164, v164, v165
	v_add_f32_e32 v149, v162, v164
	v_add_f32_e32 v166, v166, v167
	v_add_f32_e32 v168, v168, v169
	v_add_f32_e32 v171, v166, v168
	global_load_dwordx4 v[154:157], v139, s[2:3]
	global_load_dwordx4 v[158:161], v139, s[2:3] offset:1024
	global_load_dwordx4 v[162:165], v139, s[2:3] offset:2048
	global_load_dwordx4 v[166:169], v139, s[2:3] offset:3072
	v_mov_b32_e32 v170, v147
	s_nop 1
	v_permlane16_swap_b32_e32 v170, v147
	v_add_f32_e32 v147, v170, v147
	v_mov_b32_e32 v170, v148
	s_nop 1
	v_permlane16_swap_b32_e32 v170, v148
	v_add_f32_e32 v148, v170, v148
	v_mov_b32_e32 v170, v149
	s_nop 1
	v_permlane16_swap_b32_e32 v170, v149
	v_add_f32_e32 v149, v170, v149
	v_mov_b32_e32 v170, v171
	s_nop 1
	v_permlane16_swap_b32_e32 v170, v171
	v_add_f32_e32 v171, v170, v171
	v_mov_b32_e32 v170, v147
	s_nop 1
	v_permlane32_swap_b32_e32 v170, v147
	v_add_f32_e32 v147, v170, v147
	v_mov_b32_e32 v170, v148
	s_nop 1
	v_permlane32_swap_b32_e32 v170, v148
	v_add_f32_e32 v148, v170, v148
	v_mov_b32_e32 v170, v149
	s_nop 1
	v_permlane32_swap_b32_e32 v170, v149
	v_add_f32_e32 v149, v170, v149
	v_mov_b32_e32 v170, v171
	s_nop 1
	v_permlane32_swap_b32_e32 v170, v171
	v_add_f32_e32 v171, v170, v171
	v_fmamk_f32 v147, v147, 0x3a800000, v176
	v_fmamk_f32 v148, v148, 0x3a800000, v176
	v_fmamk_f32 v149, v149, 0x3a800000, v176
	v_fmamk_f32 v171, v171, 0x3a800000, v176
	v_rsq_f32_e32 v147, v147
	v_rsq_f32_e32 v148, v148
	v_rsq_f32_e32 v149, v149
	v_rsq_f32_e32 v171, v171
	s_nop 0
	v_mul_f32_e32 v147, 0x3db8aa3b, v147
	v_mul_f32_e32 v148, 0x3db8aa3b, v148
	v_mul_f32_e32 v149, 0x3db8aa3b, v149
	v_mul_f32_e32 v171, 0x3db8aa3b, v171
	s_waitcnt vmcnt(0)
	v_add_f32_e32 v154, v154, v155
	v_add_f32_e32 v156, v156, v157
	v_add_f32_e32 v154, v154, v156
	v_add_f32_e32 v158, v158, v159
	v_add_f32_e32 v160, v160, v161
	v_add_f32_e32 v158, v158, v160
	v_add_f32_e32 v162, v162, v163
	v_add_f32_e32 v164, v164, v165
	v_add_f32_e32 v162, v162, v164
	v_add_f32_e32 v166, v166, v167
	v_add_f32_e32 v168, v168, v169
	v_add_f32_e32 v166, v166, v168
	v_mov_b32_e32 v170, v154
	s_nop 1
	v_permlane16_swap_b32_e32 v170, v154
	v_add_f32_e32 v154, v170, v154
	v_mov_b32_e32 v170, v158
	s_nop 1
	v_permlane16_swap_b32_e32 v170, v158
	v_add_f32_e32 v158, v170, v158
	v_mov_b32_e32 v170, v162
	s_nop 1
	v_permlane16_swap_b32_e32 v170, v162
	v_add_f32_e32 v162, v170, v162
	v_mov_b32_e32 v170, v166
	s_nop 1
	v_permlane16_swap_b32_e32 v170, v166
	v_add_f32_e32 v166, v170, v166
	v_mov_b32_e32 v170, v154
	s_nop 1
	v_permlane32_swap_b32_e32 v170, v154
	v_add_f32_e32 v154, v170, v154
	v_mov_b32_e32 v170, v158
	s_nop 1
	v_permlane32_swap_b32_e32 v170, v158
	v_add_f32_e32 v158, v170, v158
	v_mov_b32_e32 v170, v162
	s_nop 1
	v_permlane32_swap_b32_e32 v170, v162
	v_add_f32_e32 v162, v170, v162
	v_mov_b32_e32 v170, v166
	s_nop 1
	v_permlane32_swap_b32_e32 v170, v166
	v_add_f32_e32 v166, v170, v166
	v_fmamk_f32 v154, v154, 0x3a800000, v176
	v_fmamk_f32 v158, v158, 0x3a800000, v176
	v_fmamk_f32 v162, v162, 0x3a800000, v176
	v_fmamk_f32 v166, v166, 0x3a800000, v176
	v_rsq_f32_e32 v154, v154
	v_rsq_f32_e32 v158, v158
	v_rsq_f32_e32 v162, v162
	v_rsq_f32_e32 v166, v166
	s_nop 0
	v_mul_f32_e32 v154, 0x3db8aa3b, v154
	v_mul_f32_e32 v158, 0x3db8aa3b, v158
	v_mul_f32_e32 v162, 0x3db8aa3b, v162
	v_mul_f32_e32 v166, 0x3db8aa3b, v166
	v_mul_f32_e32 v126, v126, v147
	v_mul_f32_e32 v127, v127, v147
	v_mul_f32_e32 v128, v128, v147
	v_mul_f32_e32 v129, v129, v147
	v_mul_f32_e32 v122, v122, v147
	v_mul_f32_e32 v123, v123, v147
	v_mul_f32_e32 v124, v124, v147
	v_mul_f32_e32 v125, v125, v147
	v_cvt_pk_bf16_f32 v126, v126, v127
	v_cvt_pk_bf16_f32 v127, v128, v129
	v_cvt_pk_bf16_f32 v128, v122, v123
	v_cvt_pk_bf16_f32 v129, v124, v125
	global_store_dwordx4 v138, v[126:129], s[54:55]
	v_mul_f32_e32 v118, v118, v147
	v_mul_f32_e32 v119, v119, v147
	v_mul_f32_e32 v120, v120, v147
	v_mul_f32_e32 v121, v121, v147
	v_mul_f32_e32 v114, v114, v147
	v_mul_f32_e32 v115, v115, v147
	v_mul_f32_e32 v116, v116, v147
	v_mul_f32_e32 v117, v117, v147
	v_cvt_pk_bf16_f32 v118, v118, v119
	v_cvt_pk_bf16_f32 v119, v120, v121
	v_cvt_pk_bf16_f32 v120, v114, v115
	v_cvt_pk_bf16_f32 v121, v116, v117
	global_store_dwordx4 v138, v[118:121], s[54:55] offset:256
	v_add_u32_e32 v138, 0x8000, v138
	v_mul_f32_e32 v110, v110, v148
	v_mul_f32_e32 v111, v111, v148
	v_mul_f32_e32 v112, v112, v148
	v_mul_f32_e32 v113, v113, v148
	v_mul_f32_e32 v106, v106, v148
	v_mul_f32_e32 v107, v107, v148
	v_mul_f32_e32 v108, v108, v148
	v_mul_f32_e32 v109, v109, v148
	v_cvt_pk_bf16_f32 v110, v110, v111
	v_cvt_pk_bf16_f32 v111, v112, v113
	v_cvt_pk_bf16_f32 v112, v106, v107
	v_cvt_pk_bf16_f32 v113, v108, v109
	global_store_dwordx4 v138, v[110:113], s[54:55]
	v_mul_f32_e32 v102, v102, v148
	v_mul_f32_e32 v103, v103, v148
	v_mul_f32_e32 v104, v104, v148
	v_mul_f32_e32 v105, v105, v148
	v_mul_f32_e32 v98, v98, v148
	v_mul_f32_e32 v99, v99, v148
	v_mul_f32_e32 v100, v100, v148
	v_mul_f32_e32 v101, v101, v148
	v_cvt_pk_bf16_f32 v102, v102, v103
	v_cvt_pk_bf16_f32 v103, v104, v105
	v_cvt_pk_bf16_f32 v104, v98, v99
	v_cvt_pk_bf16_f32 v105, v100, v101
	global_store_dwordx4 v138, v[102:105], s[54:55] offset:256
	v_add_u32_e32 v138, 0x8000, v138
	v_mul_f32_e32 v94, v94, v149
	v_mul_f32_e32 v95, v95, v149
	v_mul_f32_e32 v96, v96, v149
	v_mul_f32_e32 v97, v97, v149
	v_mul_f32_e32 v90, v90, v149
	v_mul_f32_e32 v91, v91, v149
	v_mul_f32_e32 v92, v92, v149
	v_mul_f32_e32 v93, v93, v149
	v_cvt_pk_bf16_f32 v94, v94, v95
	v_cvt_pk_bf16_f32 v95, v96, v97
	v_cvt_pk_bf16_f32 v96, v90, v91
	v_cvt_pk_bf16_f32 v97, v92, v93
	global_store_dwordx4 v138, v[94:97], s[54:55]
	v_mul_f32_e32 v86, v86, v149
	v_mul_f32_e32 v87, v87, v149
	v_mul_f32_e32 v88, v88, v149
	v_mul_f32_e32 v89, v89, v149
	v_mul_f32_e32 v82, v82, v149
	v_mul_f32_e32 v83, v83, v149
	v_mul_f32_e32 v84, v84, v149
	v_mul_f32_e32 v85, v85, v149
	v_cvt_pk_bf16_f32 v86, v86, v87
	v_cvt_pk_bf16_f32 v87, v88, v89
	v_cvt_pk_bf16_f32 v88, v82, v83
	v_cvt_pk_bf16_f32 v89, v84, v85
	global_store_dwordx4 v138, v[86:89], s[54:55] offset:256
	v_add_u32_e32 v138, 0x8000, v138
	v_mul_f32_e32 v78, v78, v171
	v_mul_f32_e32 v79, v79, v171
	v_mul_f32_e32 v80, v80, v171
	v_mul_f32_e32 v81, v81, v171
	v_mul_f32_e32 v74, v74, v171
	v_mul_f32_e32 v75, v75, v171
	v_mul_f32_e32 v76, v76, v171
	v_mul_f32_e32 v77, v77, v171
	v_cvt_pk_bf16_f32 v78, v78, v79
	v_cvt_pk_bf16_f32 v79, v80, v81
	v_cvt_pk_bf16_f32 v80, v74, v75
	v_cvt_pk_bf16_f32 v81, v76, v77
	global_store_dwordx4 v138, v[78:81], s[54:55]
	v_mul_f32_e32 v70, v70, v171
	v_mul_f32_e32 v71, v71, v171
	v_mul_f32_e32 v72, v72, v171
	v_mul_f32_e32 v73, v73, v171
	v_mul_f32_e32 v66, v66, v171
	v_mul_f32_e32 v67, v67, v171
	v_mul_f32_e32 v68, v68, v171
	v_mul_f32_e32 v69, v69, v171
	v_cvt_pk_bf16_f32 v70, v70, v71
	v_cvt_pk_bf16_f32 v71, v72, v73
	v_cvt_pk_bf16_f32 v72, v66, v67
	v_cvt_pk_bf16_f32 v73, v68, v69
	global_store_dwordx4 v138, v[70:73], s[54:55] offset:256
	v_add_u32_e32 v138, 0x28000, v138
	v_mul_f32_e32 v60, v60, v154
	v_mul_f32_e32 v61, v61, v154
	v_mul_f32_e32 v62, v62, v154
	v_mul_f32_e32 v63, v63, v154
	v_mul_f32_e32 v56, v56, v154
	v_mul_f32_e32 v57, v57, v154
	v_mul_f32_e32 v58, v58, v154
	v_mul_f32_e32 v59, v59, v154
	v_cvt_pk_bf16_f32 v60, v60, v61
	v_cvt_pk_bf16_f32 v61, v62, v63
	v_cvt_pk_bf16_f32 v62, v56, v57
	v_cvt_pk_bf16_f32 v63, v58, v59
	global_store_dwordx4 v138, v[60:63], s[54:55]
	v_mul_f32_e32 v52, v52, v154
	v_mul_f32_e32 v53, v53, v154
	v_mul_f32_e32 v54, v54, v154
	v_mul_f32_e32 v55, v55, v154
	v_mul_f32_e32 v48, v48, v154
	v_mul_f32_e32 v49, v49, v154
	v_mul_f32_e32 v50, v50, v154
	v_mul_f32_e32 v51, v51, v154
	v_cvt_pk_bf16_f32 v52, v52, v53
	v_cvt_pk_bf16_f32 v53, v54, v55
	v_cvt_pk_bf16_f32 v54, v48, v49
	v_cvt_pk_bf16_f32 v55, v50, v51
	global_store_dwordx4 v138, v[52:55], s[54:55] offset:256
	v_add_u32_e32 v138, 0x8000, v138
	v_mul_f32_e32 v44, v44, v158
	v_mul_f32_e32 v45, v45, v158
	v_mul_f32_e32 v46, v46, v158
	v_mul_f32_e32 v47, v47, v158
	v_mul_f32_e32 v40, v40, v158
	v_mul_f32_e32 v41, v41, v158
	v_mul_f32_e32 v42, v42, v158
	v_mul_f32_e32 v43, v43, v158
	v_cvt_pk_bf16_f32 v44, v44, v45
	v_cvt_pk_bf16_f32 v45, v46, v47
	v_cvt_pk_bf16_f32 v46, v40, v41
	v_cvt_pk_bf16_f32 v47, v42, v43
	global_store_dwordx4 v138, v[44:47], s[54:55]
	v_mul_f32_e32 v36, v36, v158
	v_mul_f32_e32 v37, v37, v158
	v_mul_f32_e32 v38, v38, v158
	v_mul_f32_e32 v39, v39, v158
	v_mul_f32_e32 v32, v32, v158
	v_mul_f32_e32 v33, v33, v158
	v_mul_f32_e32 v34, v34, v158
	v_mul_f32_e32 v35, v35, v158
	v_cvt_pk_bf16_f32 v36, v36, v37
	v_cvt_pk_bf16_f32 v37, v38, v39
	v_cvt_pk_bf16_f32 v38, v32, v33
	v_cvt_pk_bf16_f32 v39, v34, v35
	global_store_dwordx4 v138, v[36:39], s[54:55] offset:256
	v_add_u32_e32 v138, 0x8000, v138
	v_mul_f32_e32 v28, v28, v162
	v_mul_f32_e32 v29, v29, v162
	v_mul_f32_e32 v30, v30, v162
	v_mul_f32_e32 v31, v31, v162
	v_mul_f32_e32 v24, v24, v162
	v_mul_f32_e32 v25, v25, v162
	v_mul_f32_e32 v26, v26, v162
	v_mul_f32_e32 v27, v27, v162
	v_cvt_pk_bf16_f32 v28, v28, v29
	v_cvt_pk_bf16_f32 v29, v30, v31
	v_cvt_pk_bf16_f32 v30, v24, v25
	v_cvt_pk_bf16_f32 v31, v26, v27
	global_store_dwordx4 v138, v[28:31], s[54:55]
	v_mul_f32_e32 v20, v20, v162
	v_mul_f32_e32 v21, v21, v162
	v_mul_f32_e32 v22, v22, v162
	v_mul_f32_e32 v23, v23, v162
	v_mul_f32_e32 v16, v16, v162
	v_mul_f32_e32 v17, v17, v162
	v_mul_f32_e32 v18, v18, v162
	v_mul_f32_e32 v19, v19, v162
	v_cvt_pk_bf16_f32 v20, v20, v21
	v_cvt_pk_bf16_f32 v21, v22, v23
	v_cvt_pk_bf16_f32 v22, v16, v17
	v_cvt_pk_bf16_f32 v23, v18, v19
	global_store_dwordx4 v138, v[20:23], s[54:55] offset:256
	v_add_u32_e32 v138, 0x8000, v138
	v_mul_f32_e32 v12, v12, v166
	v_mul_f32_e32 v13, v13, v166
	v_mul_f32_e32 v14, v14, v166
	v_mul_f32_e32 v15, v15, v166
	v_mul_f32_e32 v8, v8, v166
	v_mul_f32_e32 v9, v9, v166
	v_mul_f32_e32 v10, v10, v166
	v_mul_f32_e32 v11, v11, v166
	v_cvt_pk_bf16_f32 v12, v12, v13
	v_cvt_pk_bf16_f32 v13, v14, v15
	v_cvt_pk_bf16_f32 v14, v8, v9
	v_cvt_pk_bf16_f32 v15, v10, v11
	global_store_dwordx4 v138, v[12:15], s[54:55]
	v_mul_f32_e32 v4, v4, v166
	v_mul_f32_e32 v5, v5, v166
	v_mul_f32_e32 v6, v6, v166
	v_mul_f32_e32 v7, v7, v166
	v_mul_f32_e32 v0, v0, v166
	v_mul_f32_e32 v1, v1, v166
	v_mul_f32_e32 v2, v2, v166
	v_mul_f32_e32 v3, v3, v166
	v_cvt_pk_bf16_f32 v4, v4, v5
	v_cvt_pk_bf16_f32 v5, v6, v7
	v_cvt_pk_bf16_f32 v6, v0, v1
	v_cvt_pk_bf16_f32 v7, v2, v3
	global_store_dwordx4 v138, v[4:7], s[54:55] offset:256
	s_andn2_b64 vcc, exec, s[38:39]
	s_mov_b64 s[36:37], -1
	s_branch .Lxq_done
.Lxq_done:
	s_cbranch_vccnz .LBB0_58
	s_andn2_b64 vcc, exec, s[0:1]
	s_cbranch_vccnz .LBB0_57
	s_barrier
	s_branch .LBB0_57

.LBB0_110:
	v_readlane_b32 s4, v250, 25
	v_mbcnt_lo_u32_b32 v138, -1, 0
	v_mbcnt_hi_u32_b32 v138, -1, v138
	s_nop 1
	s_lshr_b32 s5, s4, 8
	s_bfe_u32 s4, s4, 0x20006
	v_and_b32_e32 v139, 15, v138
	v_lshrrev_b32_e32 v148, 4, v138
	s_lshl_b32 s70, s29, 8
	s_lshl_b32 s5, s5, 6
	s_add_u32 s5, s5, s70
	v_add_u32_e32 v139, s5, v139
	v_lshlrev_b32_e32 v149, 6, v139
	v_lshlrev_b32_e32 v150, 11, v139
	v_lshl_add_u32 v150, v148, 4, v150
	s_lshl_b32 s71, s4, 6
	v_add_u32_e32 v150, s71, v150
	v_mov_b32_e32 v151, v150
	s_lshl_b32 s70, s28, 9
	s_add_u32 s74, s30, s70
	s_addc_u32 s75, s31, 0
	s_lshl_b32 s57, s28, 2
	s_lshl_b32 s56, s28, 4
	s_lshl_b32 s76, s4, 2
	s_add_u32 s56, s56, s76
	v_readlane_b32 s28, v250, 26
	v_readlane_b32 s29, v250, 27
	global_load_dwordx4 v[184:187], v150, s[74:75]
	global_load_dwordx4 v[188:191], v150, s[74:75] offset:256
	v_add_u32_e32 v150, 0x8000, v150
	global_load_dwordx4 v[192:195], v150, s[74:75]
	global_load_dwordx4 v[196:199], v150, s[74:75] offset:256
	v_add_u32_e32 v150, 0x8000, v150
	global_load_dwordx4 v[200:203], v150, s[74:75]
	global_load_dwordx4 v[204:207], v150, s[74:75] offset:256
	v_add_u32_e32 v150, 0x8000, v150
	global_load_dwordx4 v[208:211], v150, s[74:75]
	global_load_dwordx4 v[212:215], v150, s[74:75] offset:256
	v_add_u32_e32 v150, 0x28000, v150
	global_load_dwordx4 v[216:219], v150, s[74:75]
	global_load_dwordx4 v[220:223], v150, s[74:75] offset:256
	v_add_u32_e32 v150, 0x8000, v150
	global_load_dwordx4 v[224:227], v150, s[74:75]
	global_load_dwordx4 v[228:231], v150, s[74:75] offset:256
	v_add_u32_e32 v150, 0x8000, v150
	global_load_dwordx4 v[232:235], v150, s[74:75]
	global_load_dwordx4 v[236:239], v150, s[74:75] offset:256
	v_add_u32_e32 v150, 0x8000, v150
	global_load_dwordx4 v[240:243], v150, s[74:75]
	global_load_dwordx4 v[244:247], v150, s[74:75] offset:256
	s_waitcnt vmcnt(15)
	v_lshlrev_b32_e32 v182, 16, v184
	v_and_b32_e32 v183, 0xffff0000, v184
	v_pk_add_f32 v[126:127], v[126:127], v[182:183]
	v_lshlrev_b32_e32 v248, 16, v185
	v_and_b32_e32 v249, 0xffff0000, v185
	v_pk_add_f32 v[128:129], v[128:129], v[248:249]
	v_lshlrev_b32_e32 v138, 16, v186
	v_and_b32_e32 v139, 0xffff0000, v186
	v_pk_add_f32 v[122:123], v[122:123], v[138:139]
	v_lshlrev_b32_e32 v182, 16, v187
	v_and_b32_e32 v183, 0xffff0000, v187
	v_pk_add_f32 v[124:125], v[124:125], v[182:183]
	v_cvt_pk_bf16_f32 v126, v126, v127
	v_cvt_pk_bf16_f32 v127, v128, v129
	v_cvt_pk_bf16_f32 v128, v122, v123
	v_cvt_pk_bf16_f32 v129, v124, v125
	global_store_dwordx4 v151, v[126:129], s[74:75]
	v_lshlrev_b32_e32 v184, 16, v126
	v_lshlrev_b32_e32 v185, 16, v127
	v_lshlrev_b32_e32 v186, 16, v128
	v_lshlrev_b32_e32 v187, 16, v129
	v_and_b32_e32 v122, 0xffff0000, v126
	v_and_b32_e32 v123, 0xffff0000, v127
	v_and_b32_e32 v124, 0xffff0000, v128
	v_and_b32_e32 v125, 0xffff0000, v129
	v_mul_f32_e32 v122, v122, v122
	v_mul_f32_e32 v123, v123, v123
	v_mul_f32_e32 v124, v124, v124
	v_mul_f32_e32 v125, v125, v125
	v_fmac_f32_e32 v122, v184, v184
	v_fmac_f32_e32 v123, v185, v185
	v_fmac_f32_e32 v124, v186, v186
	v_fmac_f32_e32 v125, v187, v187
	v_add_f32_e32 v122, v122, v123
	v_add_f32_e32 v122, v122, v124
	v_add_f32_e32 v122, v122, v125
	s_waitcnt vmcnt(15)
	v_lshlrev_b32_e32 v182, 16, v188
	v_and_b32_e32 v183, 0xffff0000, v188
	v_pk_add_f32 v[118:119], v[118:119], v[182:183]
	v_lshlrev_b32_e32 v248, 16, v189
	v_and_b32_e32 v249, 0xffff0000, v189
	v_pk_add_f32 v[120:121], v[120:121], v[248:249]
	v_lshlrev_b32_e32 v138, 16, v190
	v_and_b32_e32 v139, 0xffff0000, v190
	v_pk_add_f32 v[114:115], v[114:115], v[138:139]
	v_lshlrev_b32_e32 v182, 16, v191
	v_and_b32_e32 v183, 0xffff0000, v191
	v_pk_add_f32 v[116:117], v[116:117], v[182:183]
	v_cvt_pk_bf16_f32 v118, v118, v119
	v_cvt_pk_bf16_f32 v119, v120, v121
	v_cvt_pk_bf16_f32 v120, v114, v115
	v_cvt_pk_bf16_f32 v121, v116, v117
	global_store_dwordx4 v151, v[118:121], s[74:75] offset:256
	v_lshlrev_b32_e32 v188, 16, v118
	v_lshlrev_b32_e32 v189, 16, v119
	v_lshlrev_b32_e32 v190, 16, v120
	v_lshlrev_b32_e32 v191, 16, v121
	v_and_b32_e32 v114, 0xffff0000, v118
	v_and_b32_e32 v115, 0xffff0000, v119
	v_and_b32_e32 v116, 0xffff0000, v120
	v_and_b32_e32 v117, 0xffff0000, v121
	v_mul_f32_e32 v114, v114, v114
	v_mul_f32_e32 v115, v115, v115
	v_mul_f32_e32 v116, v116, v116
	v_mul_f32_e32 v117, v117, v117
	v_fmac_f32_e32 v114, v188, v188
	v_fmac_f32_e32 v115, v189, v189
	v_fmac_f32_e32 v116, v190, v190
	v_fmac_f32_e32 v117, v191, v191
	v_add_f32_e32 v114, v114, v115
	v_add_f32_e32 v114, v114, v116
	v_add_f32_e32 v114, v114, v117
	v_add_f32_e32 v122, v122, v114
	v_add_u32_e32 v151, 0x8000, v151
	s_waitcnt vmcnt(15)
	v_lshlrev_b32_e32 v182, 16, v192
	v_and_b32_e32 v183, 0xffff0000, v192
	v_pk_add_f32 v[110:111], v[110:111], v[182:183]
	v_lshlrev_b32_e32 v248, 16, v193
	v_and_b32_e32 v249, 0xffff0000, v193
	v_pk_add_f32 v[112:113], v[112:113], v[248:249]
	v_lshlrev_b32_e32 v138, 16, v194
	v_and_b32_e32 v139, 0xffff0000, v194
	v_pk_add_f32 v[106:107], v[106:107], v[138:139]
	v_lshlrev_b32_e32 v182, 16, v195
	v_and_b32_e32 v183, 0xffff0000, v195
	v_pk_add_f32 v[108:109], v[108:109], v[182:183]
	v_cvt_pk_bf16_f32 v110, v110, v111
	v_cvt_pk_bf16_f32 v111, v112, v113
	v_cvt_pk_bf16_f32 v112, v106, v107
	v_cvt_pk_bf16_f32 v113, v108, v109
	global_store_dwordx4 v151, v[110:113], s[74:75]
	v_lshlrev_b32_e32 v192, 16, v110
	v_lshlrev_b32_e32 v193, 16, v111
	v_lshlrev_b32_e32 v194, 16, v112
	v_lshlrev_b32_e32 v195, 16, v113
	v_and_b32_e32 v106, 0xffff0000, v110
	v_and_b32_e32 v107, 0xffff0000, v111
	v_and_b32_e32 v108, 0xffff0000, v112
	v_and_b32_e32 v109, 0xffff0000, v113
	v_mul_f32_e32 v106, v106, v106
	v_mul_f32_e32 v107, v107, v107
	v_mul_f32_e32 v108, v108, v108
	v_mul_f32_e32 v109, v109, v109
	v_fmac_f32_e32 v106, v192, v192
	v_fmac_f32_e32 v107, v193, v193
	v_fmac_f32_e32 v108, v194, v194
	v_fmac_f32_e32 v109, v195, v195
	v_add_f32_e32 v106, v106, v107
	v_add_f32_e32 v106, v106, v108
	v_add_f32_e32 v106, v106, v109
	s_waitcnt vmcnt(15)
	v_lshlrev_b32_e32 v182, 16, v196
	v_and_b32_e32 v183, 0xffff0000, v196
	v_pk_add_f32 v[102:103], v[102:103], v[182:183]
	v_lshlrev_b32_e32 v248, 16, v197
	v_and_b32_e32 v249, 0xffff0000, v197
	v_pk_add_f32 v[104:105], v[104:105], v[248:249]
	v_lshlrev_b32_e32 v138, 16, v198
	v_and_b32_e32 v139, 0xffff0000, v198
	v_pk_add_f32 v[98:99], v[98:99], v[138:139]
	v_lshlrev_b32_e32 v182, 16, v199
	v_and_b32_e32 v183, 0xffff0000, v199
	v_pk_add_f32 v[100:101], v[100:101], v[182:183]
	v_cvt_pk_bf16_f32 v102, v102, v103
	v_cvt_pk_bf16_f32 v103, v104, v105
	v_cvt_pk_bf16_f32 v104, v98, v99
	v_cvt_pk_bf16_f32 v105, v100, v101
	global_store_dwordx4 v151, v[102:105], s[74:75] offset:256
	v_lshlrev_b32_e32 v196, 16, v102
	v_lshlrev_b32_e32 v197, 16, v103
	v_lshlrev_b32_e32 v198, 16, v104
	v_lshlrev_b32_e32 v199, 16, v105
	v_and_b32_e32 v98, 0xffff0000, v102
	v_and_b32_e32 v99, 0xffff0000, v103
	v_and_b32_e32 v100, 0xffff0000, v104
	v_and_b32_e32 v101, 0xffff0000, v105
	v_mul_f32_e32 v98, v98, v98
	v_mul_f32_e32 v99, v99, v99
	v_mul_f32_e32 v100, v100, v100
	v_mul_f32_e32 v101, v101, v101
	v_fmac_f32_e32 v98, v196, v196
	v_fmac_f32_e32 v99, v197, v197
	v_fmac_f32_e32 v100, v198, v198
	v_fmac_f32_e32 v101, v199, v199
	v_add_f32_e32 v98, v98, v99
	v_add_f32_e32 v98, v98, v100
	v_add_f32_e32 v98, v98, v101
	v_add_f32_e32 v106, v106, v98
	v_add_u32_e32 v151, 0x8000, v151
	s_waitcnt vmcnt(15)
	v_lshlrev_b32_e32 v182, 16, v200
	v_and_b32_e32 v183, 0xffff0000, v200
	v_pk_add_f32 v[94:95], v[94:95], v[182:183]
	v_lshlrev_b32_e32 v248, 16, v201
	v_and_b32_e32 v249, 0xffff0000, v201
	v_pk_add_f32 v[96:97], v[96:97], v[248:249]
	v_lshlrev_b32_e32 v138, 16, v202
	v_and_b32_e32 v139, 0xffff0000, v202
	v_pk_add_f32 v[90:91], v[90:91], v[138:139]
	v_lshlrev_b32_e32 v182, 16, v203
	v_and_b32_e32 v183, 0xffff0000, v203
	v_pk_add_f32 v[92:93], v[92:93], v[182:183]
	v_cvt_pk_bf16_f32 v94, v94, v95
	v_cvt_pk_bf16_f32 v95, v96, v97
	v_cvt_pk_bf16_f32 v96, v90, v91
	v_cvt_pk_bf16_f32 v97, v92, v93
	global_store_dwordx4 v151, v[94:97], s[74:75]
	v_lshlrev_b32_e32 v200, 16, v94
	v_lshlrev_b32_e32 v201, 16, v95
	v_lshlrev_b32_e32 v202, 16, v96
	v_lshlrev_b32_e32 v203, 16, v97
	v_and_b32_e32 v90, 0xffff0000, v94
	v_and_b32_e32 v91, 0xffff0000, v95
	v_and_b32_e32 v92, 0xffff0000, v96
	v_and_b32_e32 v93, 0xffff0000, v97
	v_mul_f32_e32 v90, v90, v90
	v_mul_f32_e32 v91, v91, v91
	v_mul_f32_e32 v92, v92, v92
	v_mul_f32_e32 v93, v93, v93
	v_fmac_f32_e32 v90, v200, v200
	v_fmac_f32_e32 v91, v201, v201
	v_fmac_f32_e32 v92, v202, v202
	v_fmac_f32_e32 v93, v203, v203
	v_add_f32_e32 v90, v90, v91
	v_add_f32_e32 v90, v90, v92
	v_add_f32_e32 v90, v90, v93
	s_waitcnt vmcnt(15)
	v_lshlrev_b32_e32 v182, 16, v204
	v_and_b32_e32 v183, 0xffff0000, v204
	v_pk_add_f32 v[86:87], v[86:87], v[182:183]
	v_lshlrev_b32_e32 v248, 16, v205
	v_and_b32_e32 v249, 0xffff0000, v205
	v_pk_add_f32 v[88:89], v[88:89], v[248:249]
	v_lshlrev_b32_e32 v138, 16, v206
	v_and_b32_e32 v139, 0xffff0000, v206
	v_pk_add_f32 v[82:83], v[82:83], v[138:139]
	v_lshlrev_b32_e32 v182, 16, v207
	v_and_b32_e32 v183, 0xffff0000, v207
	v_pk_add_f32 v[84:85], v[84:85], v[182:183]
	v_cvt_pk_bf16_f32 v86, v86, v87
	v_cvt_pk_bf16_f32 v87, v88, v89
	v_cvt_pk_bf16_f32 v88, v82, v83
	v_cvt_pk_bf16_f32 v89, v84, v85
	global_store_dwordx4 v151, v[86:89], s[74:75] offset:256
	v_lshlrev_b32_e32 v204, 16, v86
	v_lshlrev_b32_e32 v205, 16, v87
	v_lshlrev_b32_e32 v206, 16, v88
	v_lshlrev_b32_e32 v207, 16, v89
	v_and_b32_e32 v82, 0xffff0000, v86
	v_and_b32_e32 v83, 0xffff0000, v87
	v_and_b32_e32 v84, 0xffff0000, v88
	v_and_b32_e32 v85, 0xffff0000, v89
	v_mul_f32_e32 v82, v82, v82
	v_mul_f32_e32 v83, v83, v83
	v_mul_f32_e32 v84, v84, v84
	v_mul_f32_e32 v85, v85, v85
	v_fmac_f32_e32 v82, v204, v204
	v_fmac_f32_e32 v83, v205, v205
	v_fmac_f32_e32 v84, v206, v206
	v_fmac_f32_e32 v85, v207, v207
	v_add_f32_e32 v82, v82, v83
	v_add_f32_e32 v82, v82, v84
	v_add_f32_e32 v82, v82, v85
	v_add_f32_e32 v90, v90, v82
	v_add_u32_e32 v151, 0x8000, v151
	s_waitcnt vmcnt(15)
	v_lshlrev_b32_e32 v182, 16, v208
	v_and_b32_e32 v183, 0xffff0000, v208
	v_pk_add_f32 v[78:79], v[78:79], v[182:183]
	v_lshlrev_b32_e32 v248, 16, v209
	v_and_b32_e32 v249, 0xffff0000, v209
	v_pk_add_f32 v[80:81], v[80:81], v[248:249]
	v_lshlrev_b32_e32 v138, 16, v210
	v_and_b32_e32 v139, 0xffff0000, v210
	v_pk_add_f32 v[74:75], v[74:75], v[138:139]
	v_lshlrev_b32_e32 v182, 16, v211
	v_and_b32_e32 v183, 0xffff0000, v211
	v_pk_add_f32 v[76:77], v[76:77], v[182:183]
	v_cvt_pk_bf16_f32 v78, v78, v79
	v_cvt_pk_bf16_f32 v79, v80, v81
	v_cvt_pk_bf16_f32 v80, v74, v75
	v_cvt_pk_bf16_f32 v81, v76, v77
	global_store_dwordx4 v151, v[78:81], s[74:75]
	v_lshlrev_b32_e32 v208, 16, v78
	v_lshlrev_b32_e32 v209, 16, v79
	v_lshlrev_b32_e32 v210, 16, v80
	v_lshlrev_b32_e32 v211, 16, v81
	v_and_b32_e32 v74, 0xffff0000, v78
	v_and_b32_e32 v75, 0xffff0000, v79
	v_and_b32_e32 v76, 0xffff0000, v80
	v_and_b32_e32 v77, 0xffff0000, v81
	v_mul_f32_e32 v74, v74, v74
	v_mul_f32_e32 v75, v75, v75
	v_mul_f32_e32 v76, v76, v76
	v_mul_f32_e32 v77, v77, v77
	v_fmac_f32_e32 v74, v208, v208
	v_fmac_f32_e32 v75, v209, v209
	v_fmac_f32_e32 v76, v210, v210
	v_fmac_f32_e32 v77, v211, v211
	v_add_f32_e32 v74, v74, v75
	v_add_f32_e32 v74, v74, v76
	v_add_f32_e32 v74, v74, v77
	s_waitcnt vmcnt(15)
	v_lshlrev_b32_e32 v182, 16, v212
	v_and_b32_e32 v183, 0xffff0000, v212
	v_pk_add_f32 v[70:71], v[70:71], v[182:183]
	v_lshlrev_b32_e32 v248, 16, v213
	v_and_b32_e32 v249, 0xffff0000, v213
	v_pk_add_f32 v[72:73], v[72:73], v[248:249]
	v_lshlrev_b32_e32 v138, 16, v214
	v_and_b32_e32 v139, 0xffff0000, v214
	v_pk_add_f32 v[66:67], v[66:67], v[138:139]
	v_lshlrev_b32_e32 v182, 16, v215
	v_and_b32_e32 v183, 0xffff0000, v215
	v_pk_add_f32 v[68:69], v[68:69], v[182:183]
	v_cvt_pk_bf16_f32 v70, v70, v71
	v_cvt_pk_bf16_f32 v71, v72, v73
	v_cvt_pk_bf16_f32 v72, v66, v67
	v_cvt_pk_bf16_f32 v73, v68, v69
	global_store_dwordx4 v151, v[70:73], s[74:75] offset:256
	v_lshlrev_b32_e32 v212, 16, v70
	v_lshlrev_b32_e32 v213, 16, v71
	v_lshlrev_b32_e32 v214, 16, v72
	v_lshlrev_b32_e32 v215, 16, v73
	v_and_b32_e32 v66, 0xffff0000, v70
	v_and_b32_e32 v67, 0xffff0000, v71
	v_and_b32_e32 v68, 0xffff0000, v72
	v_and_b32_e32 v69, 0xffff0000, v73
	v_mul_f32_e32 v66, v66, v66
	v_mul_f32_e32 v67, v67, v67
	v_mul_f32_e32 v68, v68, v68
	v_mul_f32_e32 v69, v69, v69
	v_fmac_f32_e32 v66, v212, v212
	v_fmac_f32_e32 v67, v213, v213
	v_fmac_f32_e32 v68, v214, v214
	v_fmac_f32_e32 v69, v215, v215
	v_add_f32_e32 v66, v66, v67
	v_add_f32_e32 v66, v66, v68
	v_add_f32_e32 v66, v66, v69
	v_add_f32_e32 v74, v74, v66
	v_add_u32_e32 v151, 0x28000, v151
	s_waitcnt vmcnt(15)
	v_lshlrev_b32_e32 v182, 16, v216
	v_and_b32_e32 v183, 0xffff0000, v216
	v_pk_add_f32 v[60:61], v[60:61], v[182:183]
	v_lshlrev_b32_e32 v248, 16, v217
	v_and_b32_e32 v249, 0xffff0000, v217
	v_pk_add_f32 v[62:63], v[62:63], v[248:249]
	v_lshlrev_b32_e32 v138, 16, v218
	v_and_b32_e32 v139, 0xffff0000, v218
	v_pk_add_f32 v[56:57], v[56:57], v[138:139]
	v_lshlrev_b32_e32 v182, 16, v219
	v_and_b32_e32 v183, 0xffff0000, v219
	v_pk_add_f32 v[58:59], v[58:59], v[182:183]
	v_cvt_pk_bf16_f32 v60, v60, v61
	v_cvt_pk_bf16_f32 v61, v62, v63
	v_cvt_pk_bf16_f32 v62, v56, v57
	v_cvt_pk_bf16_f32 v63, v58, v59
	global_store_dwordx4 v151, v[60:63], s[74:75]
	v_lshlrev_b32_e32 v216, 16, v60
	v_lshlrev_b32_e32 v217, 16, v61
	v_lshlrev_b32_e32 v218, 16, v62
	v_lshlrev_b32_e32 v219, 16, v63
	v_and_b32_e32 v56, 0xffff0000, v60
	v_and_b32_e32 v57, 0xffff0000, v61
	v_and_b32_e32 v58, 0xffff0000, v62
	v_and_b32_e32 v59, 0xffff0000, v63
	v_mul_f32_e32 v56, v56, v56
	v_mul_f32_e32 v57, v57, v57
	v_mul_f32_e32 v58, v58, v58
	v_mul_f32_e32 v59, v59, v59
	v_fmac_f32_e32 v56, v216, v216
	v_fmac_f32_e32 v57, v217, v217
	v_fmac_f32_e32 v58, v218, v218
	v_fmac_f32_e32 v59, v219, v219
	v_add_f32_e32 v56, v56, v57
	v_add_f32_e32 v56, v56, v58
	v_add_f32_e32 v56, v56, v59
	s_waitcnt vmcnt(15)
	v_lshlrev_b32_e32 v182, 16, v220
	v_and_b32_e32 v183, 0xffff0000, v220
	v_pk_add_f32 v[52:53], v[52:53], v[182:183]
	v_lshlrev_b32_e32 v248, 16, v221
	v_and_b32_e32 v249, 0xffff0000, v221
	v_pk_add_f32 v[54:55], v[54:55], v[248:249]
	v_lshlrev_b32_e32 v138, 16, v222
	v_and_b32_e32 v139, 0xffff0000, v222
	v_pk_add_f32 v[48:49], v[48:49], v[138:139]
	v_lshlrev_b32_e32 v182, 16, v223
	v_and_b32_e32 v183, 0xffff0000, v223
	v_pk_add_f32 v[50:51], v[50:51], v[182:183]
	v_cvt_pk_bf16_f32 v52, v52, v53
	v_cvt_pk_bf16_f32 v53, v54, v55
	v_cvt_pk_bf16_f32 v54, v48, v49
	v_cvt_pk_bf16_f32 v55, v50, v51
	global_store_dwordx4 v151, v[52:55], s[74:75] offset:256
	v_lshlrev_b32_e32 v220, 16, v52
	v_lshlrev_b32_e32 v221, 16, v53
	v_lshlrev_b32_e32 v222, 16, v54
	v_lshlrev_b32_e32 v223, 16, v55
	v_and_b32_e32 v48, 0xffff0000, v52
	v_and_b32_e32 v49, 0xffff0000, v53
	v_and_b32_e32 v50, 0xffff0000, v54
	v_and_b32_e32 v51, 0xffff0000, v55
	v_mul_f32_e32 v48, v48, v48
	v_mul_f32_e32 v49, v49, v49
	v_mul_f32_e32 v50, v50, v50
	v_mul_f32_e32 v51, v51, v51
	v_fmac_f32_e32 v48, v220, v220
	v_fmac_f32_e32 v49, v221, v221
	v_fmac_f32_e32 v50, v222, v222
	v_fmac_f32_e32 v51, v223, v223
	v_add_f32_e32 v48, v48, v49
	v_add_f32_e32 v48, v48, v50
	v_add_f32_e32 v48, v48, v51
	v_add_f32_e32 v56, v56, v48
	v_add_u32_e32 v151, 0x8000, v151
	s_waitcnt vmcnt(15)
	v_lshlrev_b32_e32 v182, 16, v224
	v_and_b32_e32 v183, 0xffff0000, v224
	v_pk_add_f32 v[44:45], v[44:45], v[182:183]
	v_lshlrev_b32_e32 v248, 16, v225
	v_and_b32_e32 v249, 0xffff0000, v225
	v_pk_add_f32 v[46:47], v[46:47], v[248:249]
	v_lshlrev_b32_e32 v138, 16, v226
	v_and_b32_e32 v139, 0xffff0000, v226
	v_pk_add_f32 v[40:41], v[40:41], v[138:139]
	v_lshlrev_b32_e32 v182, 16, v227
	v_and_b32_e32 v183, 0xffff0000, v227
	v_pk_add_f32 v[42:43], v[42:43], v[182:183]
	v_cvt_pk_bf16_f32 v44, v44, v45
	v_cvt_pk_bf16_f32 v45, v46, v47
	v_cvt_pk_bf16_f32 v46, v40, v41
	v_cvt_pk_bf16_f32 v47, v42, v43
	global_store_dwordx4 v151, v[44:47], s[74:75]
	v_lshlrev_b32_e32 v224, 16, v44
	v_lshlrev_b32_e32 v225, 16, v45
	v_lshlrev_b32_e32 v226, 16, v46
	v_lshlrev_b32_e32 v227, 16, v47
	v_and_b32_e32 v40, 0xffff0000, v44
	v_and_b32_e32 v41, 0xffff0000, v45
	v_and_b32_e32 v42, 0xffff0000, v46
	v_and_b32_e32 v43, 0xffff0000, v47
	v_mul_f32_e32 v40, v40, v40
	v_mul_f32_e32 v41, v41, v41
	v_mul_f32_e32 v42, v42, v42
	v_mul_f32_e32 v43, v43, v43
	v_fmac_f32_e32 v40, v224, v224
	v_fmac_f32_e32 v41, v225, v225
	v_fmac_f32_e32 v42, v226, v226
	v_fmac_f32_e32 v43, v227, v227
	v_add_f32_e32 v40, v40, v41
	v_add_f32_e32 v40, v40, v42
	v_add_f32_e32 v40, v40, v43
	s_waitcnt vmcnt(15)
	v_lshlrev_b32_e32 v182, 16, v228
	v_and_b32_e32 v183, 0xffff0000, v228
	v_pk_add_f32 v[36:37], v[36:37], v[182:183]
	v_lshlrev_b32_e32 v248, 16, v229
	v_and_b32_e32 v249, 0xffff0000, v229
	v_pk_add_f32 v[38:39], v[38:39], v[248:249]
	v_lshlrev_b32_e32 v138, 16, v230
	v_and_b32_e32 v139, 0xffff0000, v230
	v_pk_add_f32 v[32:33], v[32:33], v[138:139]
	v_lshlrev_b32_e32 v182, 16, v231
	v_and_b32_e32 v183, 0xffff0000, v231
	v_pk_add_f32 v[34:35], v[34:35], v[182:183]
	v_cvt_pk_bf16_f32 v36, v36, v37
	v_cvt_pk_bf16_f32 v37, v38, v39
	v_cvt_pk_bf16_f32 v38, v32, v33
	v_cvt_pk_bf16_f32 v39, v34, v35
	global_store_dwordx4 v151, v[36:39], s[74:75] offset:256
	v_lshlrev_b32_e32 v228, 16, v36
	v_lshlrev_b32_e32 v229, 16, v37
	v_lshlrev_b32_e32 v230, 16, v38
	v_lshlrev_b32_e32 v231, 16, v39
	v_and_b32_e32 v32, 0xffff0000, v36
	v_and_b32_e32 v33, 0xffff0000, v37
	v_and_b32_e32 v34, 0xffff0000, v38
	v_and_b32_e32 v35, 0xffff0000, v39
	v_mul_f32_e32 v32, v32, v32
	v_mul_f32_e32 v33, v33, v33
	v_mul_f32_e32 v34, v34, v34
	v_mul_f32_e32 v35, v35, v35
	v_fmac_f32_e32 v32, v228, v228
	v_fmac_f32_e32 v33, v229, v229
	v_fmac_f32_e32 v34, v230, v230
	v_fmac_f32_e32 v35, v231, v231
	v_add_f32_e32 v32, v32, v33
	v_add_f32_e32 v32, v32, v34
	v_add_f32_e32 v32, v32, v35
	v_add_f32_e32 v40, v40, v32
	v_add_u32_e32 v151, 0x8000, v151
	s_waitcnt vmcnt(15)
	v_lshlrev_b32_e32 v182, 16, v232
	v_and_b32_e32 v183, 0xffff0000, v232
	v_pk_add_f32 v[28:29], v[28:29], v[182:183]
	v_lshlrev_b32_e32 v248, 16, v233
	v_and_b32_e32 v249, 0xffff0000, v233
	v_pk_add_f32 v[30:31], v[30:31], v[248:249]
	v_lshlrev_b32_e32 v138, 16, v234
	v_and_b32_e32 v139, 0xffff0000, v234
	v_pk_add_f32 v[24:25], v[24:25], v[138:139]
	v_lshlrev_b32_e32 v182, 16, v235
	v_and_b32_e32 v183, 0xffff0000, v235
	v_pk_add_f32 v[26:27], v[26:27], v[182:183]
	v_cvt_pk_bf16_f32 v28, v28, v29
	v_cvt_pk_bf16_f32 v29, v30, v31
	v_cvt_pk_bf16_f32 v30, v24, v25
	v_cvt_pk_bf16_f32 v31, v26, v27
	global_store_dwordx4 v151, v[28:31], s[74:75]
	v_lshlrev_b32_e32 v232, 16, v28
	v_lshlrev_b32_e32 v233, 16, v29
	v_lshlrev_b32_e32 v234, 16, v30
	v_lshlrev_b32_e32 v235, 16, v31
	v_and_b32_e32 v24, 0xffff0000, v28
	v_and_b32_e32 v25, 0xffff0000, v29
	v_and_b32_e32 v26, 0xffff0000, v30
	v_and_b32_e32 v27, 0xffff0000, v31
	v_mul_f32_e32 v24, v24, v24
	v_mul_f32_e32 v25, v25, v25
	v_mul_f32_e32 v26, v26, v26
	v_mul_f32_e32 v27, v27, v27
	v_fmac_f32_e32 v24, v232, v232
	v_fmac_f32_e32 v25, v233, v233
	v_fmac_f32_e32 v26, v234, v234
	v_fmac_f32_e32 v27, v235, v235
	v_add_f32_e32 v24, v24, v25
	v_add_f32_e32 v24, v24, v26
	v_add_f32_e32 v24, v24, v27
	s_waitcnt vmcnt(15)
	v_lshlrev_b32_e32 v182, 16, v236
	v_and_b32_e32 v183, 0xffff0000, v236
	v_pk_add_f32 v[20:21], v[20:21], v[182:183]
	v_lshlrev_b32_e32 v248, 16, v237
	v_and_b32_e32 v249, 0xffff0000, v237
	v_pk_add_f32 v[22:23], v[22:23], v[248:249]
	v_lshlrev_b32_e32 v138, 16, v238
	v_and_b32_e32 v139, 0xffff0000, v238
	v_pk_add_f32 v[16:17], v[16:17], v[138:139]
	v_lshlrev_b32_e32 v182, 16, v239
	v_and_b32_e32 v183, 0xffff0000, v239
	v_pk_add_f32 v[18:19], v[18:19], v[182:183]
	v_cvt_pk_bf16_f32 v20, v20, v21
	v_cvt_pk_bf16_f32 v21, v22, v23
	v_cvt_pk_bf16_f32 v22, v16, v17
	v_cvt_pk_bf16_f32 v23, v18, v19
	global_store_dwordx4 v151, v[20:23], s[74:75] offset:256
	v_lshlrev_b32_e32 v236, 16, v20
	v_lshlrev_b32_e32 v237, 16, v21
	v_lshlrev_b32_e32 v238, 16, v22
	v_lshlrev_b32_e32 v239, 16, v23
	v_and_b32_e32 v16, 0xffff0000, v20
	v_and_b32_e32 v17, 0xffff0000, v21
	v_and_b32_e32 v18, 0xffff0000, v22
	v_and_b32_e32 v19, 0xffff0000, v23
	v_mul_f32_e32 v16, v16, v16
	v_mul_f32_e32 v17, v17, v17
	v_mul_f32_e32 v18, v18, v18
	v_mul_f32_e32 v19, v19, v19
	v_fmac_f32_e32 v16, v236, v236
	v_fmac_f32_e32 v17, v237, v237
	v_fmac_f32_e32 v18, v238, v238
	v_fmac_f32_e32 v19, v239, v239
	v_add_f32_e32 v16, v16, v17
	v_add_f32_e32 v16, v16, v18
	v_add_f32_e32 v16, v16, v19
	v_add_f32_e32 v24, v24, v16
	v_add_u32_e32 v151, 0x8000, v151
	s_waitcnt vmcnt(15)
	v_lshlrev_b32_e32 v182, 16, v240
	v_and_b32_e32 v183, 0xffff0000, v240
	v_pk_add_f32 v[12:13], v[12:13], v[182:183]
	v_lshlrev_b32_e32 v248, 16, v241
	v_and_b32_e32 v249, 0xffff0000, v241
	v_pk_add_f32 v[14:15], v[14:15], v[248:249]
	v_lshlrev_b32_e32 v138, 16, v242
	v_and_b32_e32 v139, 0xffff0000, v242
	v_pk_add_f32 v[8:9], v[8:9], v[138:139]
	v_lshlrev_b32_e32 v182, 16, v243
	v_and_b32_e32 v183, 0xffff0000, v243
	v_pk_add_f32 v[10:11], v[10:11], v[182:183]
	v_cvt_pk_bf16_f32 v12, v12, v13
	v_cvt_pk_bf16_f32 v13, v14, v15
	v_cvt_pk_bf16_f32 v14, v8, v9
	v_cvt_pk_bf16_f32 v15, v10, v11
	global_store_dwordx4 v151, v[12:15], s[74:75]
	v_lshlrev_b32_e32 v240, 16, v12
	v_lshlrev_b32_e32 v241, 16, v13
	v_lshlrev_b32_e32 v242, 16, v14
	v_lshlrev_b32_e32 v243, 16, v15
	v_and_b32_e32 v8, 0xffff0000, v12
	v_and_b32_e32 v9, 0xffff0000, v13
	v_and_b32_e32 v10, 0xffff0000, v14
	v_and_b32_e32 v11, 0xffff0000, v15
	v_mul_f32_e32 v8, v8, v8
	v_mul_f32_e32 v9, v9, v9
	v_mul_f32_e32 v10, v10, v10
	v_mul_f32_e32 v11, v11, v11
	v_fmac_f32_e32 v8, v240, v240
	v_fmac_f32_e32 v9, v241, v241
	v_fmac_f32_e32 v10, v242, v242
	v_fmac_f32_e32 v11, v243, v243
	v_add_f32_e32 v8, v8, v9
	v_add_f32_e32 v8, v8, v10
	v_add_f32_e32 v8, v8, v11
	s_waitcnt vmcnt(15)
	v_lshlrev_b32_e32 v182, 16, v244
	v_and_b32_e32 v183, 0xffff0000, v244
	v_pk_add_f32 v[4:5], v[4:5], v[182:183]
	v_lshlrev_b32_e32 v248, 16, v245
	v_and_b32_e32 v249, 0xffff0000, v245
	v_pk_add_f32 v[6:7], v[6:7], v[248:249]
	v_lshlrev_b32_e32 v138, 16, v246
	v_and_b32_e32 v139, 0xffff0000, v246
	v_pk_add_f32 v[0:1], v[0:1], v[138:139]
	v_lshlrev_b32_e32 v182, 16, v247
	v_and_b32_e32 v183, 0xffff0000, v247
	v_pk_add_f32 v[2:3], v[2:3], v[182:183]
	v_cvt_pk_bf16_f32 v4, v4, v5
	v_cvt_pk_bf16_f32 v5, v6, v7
	v_cvt_pk_bf16_f32 v6, v0, v1
	v_cvt_pk_bf16_f32 v7, v2, v3
	global_store_dwordx4 v151, v[4:7], s[74:75] offset:256
	v_lshlrev_b32_e32 v244, 16, v4
	v_lshlrev_b32_e32 v245, 16, v5
	v_lshlrev_b32_e32 v246, 16, v6
	v_lshlrev_b32_e32 v247, 16, v7
	v_and_b32_e32 v0, 0xffff0000, v4
	v_and_b32_e32 v1, 0xffff0000, v5
	v_and_b32_e32 v2, 0xffff0000, v6
	v_and_b32_e32 v3, 0xffff0000, v7
	v_mul_f32_e32 v0, v0, v0
	v_mul_f32_e32 v1, v1, v1
	v_mul_f32_e32 v2, v2, v2
	v_mul_f32_e32 v3, v3, v3
	v_fmac_f32_e32 v0, v244, v244
	v_fmac_f32_e32 v1, v245, v245
	v_fmac_f32_e32 v2, v246, v246
	v_fmac_f32_e32 v3, v247, v247
	v_add_f32_e32 v0, v0, v1
	v_add_f32_e32 v0, v0, v2
	v_add_f32_e32 v0, v0, v3
	v_add_f32_e32 v8, v8, v0
	v_mov_b32_e32 v175, v122
	s_nop 1
	v_permlane16_swap_b32_e32 v175, v122
	v_add_f32_e32 v122, v175, v122
	v_mov_b32_e32 v175, v106
	s_nop 1
	v_permlane16_swap_b32_e32 v175, v106
	v_add_f32_e32 v106, v175, v106
	v_mov_b32_e32 v175, v90
	s_nop 1
	v_permlane16_swap_b32_e32 v175, v90
	v_add_f32_e32 v90, v175, v90
	v_mov_b32_e32 v175, v74
	s_nop 1
	v_permlane16_swap_b32_e32 v175, v74
	v_add_f32_e32 v74, v175, v74
	v_mov_b32_e32 v175, v56
	s_nop 1
	v_permlane16_swap_b32_e32 v175, v56
	v_add_f32_e32 v56, v175, v56
	v_mov_b32_e32 v175, v40
	s_nop 1
	v_permlane16_swap_b32_e32 v175, v40
	v_add_f32_e32 v40, v175, v40
	v_mov_b32_e32 v175, v24
	s_nop 1
	v_permlane16_swap_b32_e32 v175, v24
	v_add_f32_e32 v24, v175, v24
	v_mov_b32_e32 v175, v8
	s_nop 1
	v_permlane16_swap_b32_e32 v175, v8
	v_add_f32_e32 v8, v175, v8
	v_mov_b32_e32 v175, v122
	s_nop 1
	v_permlane32_swap_b32_e32 v175, v122
	v_add_f32_e32 v122, v175, v122
	v_mov_b32_e32 v175, v106
	s_nop 1
	v_permlane32_swap_b32_e32 v175, v106
	v_add_f32_e32 v106, v175, v106
	v_mov_b32_e32 v175, v90
	s_nop 1
	v_permlane32_swap_b32_e32 v175, v90
	v_add_f32_e32 v90, v175, v90
	v_mov_b32_e32 v175, v74
	s_nop 1
	v_permlane32_swap_b32_e32 v175, v74
	v_add_f32_e32 v74, v175, v74
	v_mov_b32_e32 v175, v56
	s_nop 1
	v_permlane32_swap_b32_e32 v175, v56
	v_add_f32_e32 v56, v175, v56
	v_mov_b32_e32 v175, v40
	s_nop 1
	v_permlane32_swap_b32_e32 v175, v40
	v_add_f32_e32 v40, v175, v40
	v_mov_b32_e32 v175, v24
	s_nop 1
	v_permlane32_swap_b32_e32 v175, v24
	v_add_f32_e32 v24, v175, v24
	v_mov_b32_e32 v175, v8
	s_nop 1
	v_permlane32_swap_b32_e32 v175, v8
	v_add_f32_e32 v8, v175, v8
	s_add_u32 s70, s28, s56
	s_addc_u32 s71, s29, 0
	s_and_saveexec_b64 s[4:5], s[38:39]
	s_nop 1
	global_store_dword v149, v122, s[70:71]
	v_add_u32_e32 v149, 0x400, v149
	global_store_dword v149, v106, s[70:71]
	v_add_u32_e32 v149, 0x400, v149
	global_store_dword v149, v90, s[70:71]
	v_add_u32_e32 v149, 0x400, v149
	global_store_dword v149, v74, s[70:71]
	v_add_u32_e32 v149, 0x1400, v149
	global_store_dword v149, v56, s[70:71]
	v_add_u32_e32 v149, 0x400, v149
	global_store_dword v149, v40, s[70:71]
	v_add_u32_e32 v149, 0x400, v149
	global_store_dword v149, v24, s[70:71]
	v_add_u32_e32 v149, 0x400, v149
	global_store_dword v149, v8, s[70:71]
	s_or_b64 exec, exec, s[4:5]
	s_mov_b32 s56, s57
	s_mov_b32 s57, 0
	s_lshl_b32 s76, s24, 2
	v_readlane_b32 s74, v255, 32
	v_readlane_b32 s75, v255, 33
	s_movk_i32 s78, 0xf800
	v_readlane_b32 s70, v255, 26
	v_readlane_b32 s71, v255, 27
	s_branch .Lxo_done
.Lxo_done:
	s_andn2_b64 vcc, exec, s[40:41]
	s_mov_b64 s[4:5], -1
	s_cbranch_vccnz .LBB0_99
	s_andn2_b64 vcc, exec, s[36:37]
	s_cbranch_vccnz .LBB0_98
	s_barrier
	s_branch .LBB0_98
